# prep: w_s slab conversion and score-bounds job folded into hand-written prep with early loads; gain vectors of GEMM1 mode-2 requested before reduction
# baseline (speedup 1.0000x reference)
.Lprep_new:
	s_load_dwordx4 s[4:7], s[0:1], 0x0
	s_load_dwordx4 s[8:11], s[0:1], 0x10
	s_load_dwordx4 s[12:15], s[0:1], 0x48
	s_load_dwordx2 s[16:17], s[0:1], 0x68
	s_load_dwordx4 s[20:23], s[0:1], 0x78
	s_load_dwordx2 s[24:25], s[0:1], 0x88
	s_load_dwordx4 s[28:31], s[0:1], 0x98
	s_load_dwordx2 s[60:61], s[0:1], 0x28
	s_load_dwordx2 s[62:63], s[0:1], 0x90
	s_load_dwordx4 s[64:67], s[0:1], 0x38
	s_load_dwordx4 s[68:71], s[0:1], 0x58
	s_load_dwordx2 s[98:99], s[0:1], 0xd8
	v_readfirstlane_b32 s32, v16
	v_lshrrev_b32_e32 v3, 4, v0
	v_and_b32_e32 v4, 15, v0
	v_lshlrev_b32_e32 v4, 4, v4
	v_lshlrev_b32_e32 v6, 4, v2
	v_lshlrev_b32_e32 v11, 3, v2
	s_lshl_b32 s33, s2, 3
	s_add_u32 s33, s33, s32
	s_cmpk_lt_u32 s2, 0x80
	s_cselect_b32 s34, 0, 0x180
	s_add_u32 s34, s34, s2
	s_cmpk_lt_u32 s2, 0xc0
	s_cselect_b32 s35, 6, 5
	s_cmpk_lt_u32 s2, 0x80
	s_cselect_b32 s92, 4, s35
	s_waitcnt lgkmcnt(0)
	s_cmpk_lt_u32 s2, 0x20
	s_cbranch_scc0 .Lprep_x1
	s_lshl_b32 s36, s2, 13
	s_add_u32 s60, s60, s36
	s_addc_u32 s61, s61, 0
	v_lshlrev_b32_e32 v205, 4, v0
	global_load_dwordx4 v[200:203], v205, s[60:61]
.Lprep_x1:
	s_cmpk_eq_u32 s2, 0x20
	s_cselect_b32 s36, 1, 0
	s_cmp_eq_u32 s32, 0
	s_cselect_b32 s37, 1, 0
	s_and_b32 s97, s36, s37
	s_cmp_eq_u32 s97, 0
	s_cbranch_scc1 .Lprep_x2
	v_lshlrev_b32_e32 v205, 2, v2
	global_load_dword v200, v205, s[64:65]
	global_load_dword v201, v205, s[66:67]
	global_load_dword v202, v205, s[68:69]
	global_load_dword v203, v205, s[70:71]
.Lprep_x2:
	s_add_u32 s36, s34, 0
	s_cmpk_lt_u32 s36, 0x340
	s_cbranch_scc1 .Lprep_cin_0
	s_cmpk_lt_u32 s36, 0x440
	s_cbranch_scc1 .Lprep_cout_0
	s_sub_u32 s37, s36, 0x440
	s_lshr_b32 s38, s37, 3
	s_and_b32 s39, s37, 7
	s_mov_b32 s40, 0x800
	s_mov_b64 s[42:43], s[14:15]
	s_mov_b64 s[48:49], s[12:13]
	s_mov_b64 s[50:51], s[24:25]
	s_mov_b32 s86, 0
	s_branch .Lprep_cdone_0

.Lprep_done:
	s_cmpk_lt_u32 s2, 0x20
	s_cbranch_scc0 .Lprep_y1
	v_lshrrev_b32_e32 v204, 5, v0
	v_lshl_add_u32 v204, s2, 4, v204
	v_and_b32_e32 v204, 0x7f, v204
	v_and_b32_e32 v205, 31, v0
	v_lshlrev_b32_e32 v205, 2, v205
	v_cmp_le_u32_e32 vcc, v205, v204
	s_nop 1
	v_cndmask_b32_e32 v200, 0, v200, vcc
	v_add_u32_e32 v206, 1, v205
	v_cmp_le_u32_e32 vcc, v206, v204
	s_nop 1
	v_cndmask_b32_e32 v201, 0, v201, vcc
	v_add_u32_e32 v206, 2, v205
	v_cmp_le_u32_e32 vcc, v206, v204
	s_nop 1
	v_cndmask_b32_e32 v202, 0, v202, vcc
	v_add_u32_e32 v206, 3, v205
	v_cmp_le_u32_e32 vcc, v206, v204
	s_nop 1
	v_cndmask_b32_e32 v203, 0, v203, vcc
	v_cvt_pk_bf16_f32 v200, v200, v201
	v_cvt_pk_bf16_f32 v201, v202, v203
	s_lshl_b32 s36, s2, 12
	s_add_u32 s62, s62, s36
	s_addc_u32 s63, s63, 0
	v_lshlrev_b32_e32 v205, 3, v0
	global_store_dwordx2 v205, v[200:201], s[62:63]
.Lprep_y1:
	s_cmp_eq_u32 s97, 0
	s_cbranch_scc1 .Lprep_y2
	v_and_b32_e32 v200, 0x7fffffff, v200
	v_and_b32_e32 v201, 0x7fffffff, v201
	v_and_b32_e32 v202, 0x7fffffff, v202
	v_and_b32_e32 v203, 0x7fffffff, v203
	s_nop 1
	v_max_f32_dpp v200, v200, v200 quad_perm:[1,0,3,2] row_mask:0xf bank_mask:0xf
	v_max_f32_dpp v201, v201, v201 quad_perm:[1,0,3,2] row_mask:0xf bank_mask:0xf
	v_max_f32_dpp v202, v202, v202 quad_perm:[1,0,3,2] row_mask:0xf bank_mask:0xf
	v_max_f32_dpp v203, v203, v203 quad_perm:[1,0,3,2] row_mask:0xf bank_mask:0xf
	s_nop 1
	v_max_f32_dpp v200, v200, v200 quad_perm:[2,3,0,1] row_mask:0xf bank_mask:0xf
	v_max_f32_dpp v201, v201, v201 quad_perm:[2,3,0,1] row_mask:0xf bank_mask:0xf
	v_max_f32_dpp v202, v202, v202 quad_perm:[2,3,0,1] row_mask:0xf bank_mask:0xf
	v_max_f32_dpp v203, v203, v203 quad_perm:[2,3,0,1] row_mask:0xf bank_mask:0xf
	s_nop 1
	v_max_f32_dpp v200, v200, v200 row_half_mirror row_mask:0xf bank_mask:0xf
	v_max_f32_dpp v201, v201, v201 row_half_mirror row_mask:0xf bank_mask:0xf
	v_max_f32_dpp v202, v202, v202 row_half_mirror row_mask:0xf bank_mask:0xf
	v_max_f32_dpp v203, v203, v203 row_half_mirror row_mask:0xf bank_mask:0xf
	s_nop 1
	v_max_f32_dpp v200, v200, v200 row_mirror row_mask:0xf bank_mask:0xf
	v_max_f32_dpp v201, v201, v201 row_mirror row_mask:0xf bank_mask:0xf
	v_max_f32_dpp v202, v202, v202 row_mirror row_mask:0xf bank_mask:0xf
	v_max_f32_dpp v203, v203, v203 row_mirror row_mask:0xf bank_mask:0xf
	s_nop 1
	v_readlane_b32 s36, v200, 0
	v_readlane_b32 s37, v200, 16
	v_readlane_b32 s38, v200, 32
	v_readlane_b32 s39, v200, 48
	s_nop 1
	v_mov_b32_e32 v204, s36
	v_max_f32_e32 v204, s37, v204
	v_max_f32_e32 v204, s38, v204
	v_max_f32_e32 v204, s39, v204
	v_readlane_b32 s36, v201, 0
	v_readlane_b32 s37, v201, 16
	v_readlane_b32 s38, v201, 32
	v_readlane_b32 s39, v201, 48
	s_nop 1
	v_mov_b32_e32 v205, s36
	v_max_f32_e32 v205, s37, v205
	v_max_f32_e32 v205, s38, v205
	v_max_f32_e32 v205, s39, v205
	v_readlane_b32 s36, v202, 0
	v_readlane_b32 s37, v202, 16
	v_readlane_b32 s38, v202, 32
	v_readlane_b32 s39, v202, 48
	s_nop 1
	v_mov_b32_e32 v206, s36
	v_max_f32_e32 v206, s37, v206
	v_max_f32_e32 v206, s38, v206
	v_max_f32_e32 v206, s39, v206
	v_readlane_b32 s36, v203, 0
	v_readlane_b32 s37, v203, 16
	v_readlane_b32 s38, v203, 32
	v_readlane_b32 s39, v203, 48
	s_nop 1
	v_mov_b32_e32 v207, s36
	v_max_f32_e32 v207, s37, v207
	v_max_f32_e32 v207, s38, v207
	v_max_f32_e32 v207, s39, v207
	v_mul_f32_e32 v204, 0x41000000, v204
	v_mul_f32_e32 v206, 0x41000000, v206
	v_mul_f32_e32 v204, v204, v205
	v_mul_f32_e32 v205, v206, v207
	v_mul_f32_e32 v204, 0x3fb8aa3b, v204
	v_mul_f32_e32 v205, 0x3fb8aa3b, v205
	v_mov_b32_e32 v206, 0
	s_mov_b64 s[36:37], exec
	s_mov_b64 exec, 1
	global_store_dwordx2 v206, v[204:205], s[98:99]
	s_mov_b64 exec, s[36:37]
.Lprep_y2:
	v_lshlrev_b32_e32 v234, 2, v0
	v_mbcnt_lo_u32_b32 v176, -1, 0
	s_branch .LBB0_59

.LBB0_203:
	v_mov_b32_e32 v181, 1.0
	v_cndmask_b32_e64 v130, 0, 1, s[34:35]
	v_cmp_ne_u32_e64 s[40:41], 1, v130
	s_andn2_b64 vcc, exec, s[34:35]
	v_mov_b32_e32 v180, v181
	v_mov_b32_e32 v185, v181
	v_mov_b32_e32 v184, v181
	v_mov_b32_e32 v189, v181
	v_mov_b32_e32 v188, v181
	v_mov_b32_e32 v193, v181
	v_mov_b32_e32 v192, v181
	v_mov_b32_e32 v169, v181
	v_mov_b32_e32 v168, v181
	v_mov_b32_e32 v183, v181
	v_mov_b32_e32 v182, v181
	v_mov_b32_e32 v187, v181
	v_mov_b32_e32 v186, v181
	v_mov_b32_e32 v191, v181
	v_mov_b32_e32 v190, v181
	v_mov_b32_e32 v175, v181
	v_mov_b32_e32 v174, v181
	v_mov_b32_e32 v173, v181
	v_mov_b32_e32 v172, v181
	v_mov_b32_e32 v163, v181
	v_mov_b32_e32 v162, v181
	v_mov_b32_e32 v161, v181
	v_mov_b32_e32 v160, v181
	v_mov_b32_e32 v165, v181
	v_mov_b32_e32 v164, v181
	v_mov_b32_e32 v167, v181
	v_mov_b32_e32 v166, v181
	v_mov_b32_e32 v171, v181
	v_mov_b32_e32 v170, v181
	v_mov_b32_e32 v177, v181
	v_mov_b32_e32 v176, v181
	s_cbranch_vccnz .LBB0_237
	v_lshl_add_u64 v[228:229], s[42:43], 0, v[146:147]
	v_mov_b32_e32 v230, v156
	v_mov_b32_e32 v231, v147
	v_lshl_add_u64 v[228:229], v[228:229], 0, v[230:231]
	v_bfe_u32 v230, v0, 7, 1
	v_mul_u32_u24_e32 v230, s70, v230
	v_lshlrev_b32_e32 v230, 2, v230
	v_lshl_add_u64 v[228:229], v[228:229], 0, v[230:231]
	global_load_dwordx4 v[200:203], v[228:229], off offset:16
	global_load_dwordx4 v[204:207], v[228:229], off
	v_mov_b32_e32 v230, s70
	v_lshlrev_b32_e32 v230, 3, v230
	v_lshl_add_u64 v[232:233], v[228:229], 0, v[230:231]
	global_load_dwordx4 v[216:219], v[232:233], off offset:16
	global_load_dwordx4 v[224:227], v[232:233], off
	v_and_b32_e32 v131, 64, v220
	v_xor_b32_e32 v130, 16, v220
	v_add_u32_e32 v132, 64, v131
	v_cmp_lt_i32_e32 vcc, v130, v132
	v_xor_b32_e32 v134, 32, v220
	s_nop 0
	v_cndmask_b32_e32 v130, v220, v130, vcc
	v_lshlrev_b32_e32 v131, 2, v130
	v_mul_f32_e32 v130, v123, v123
	v_fmac_f32_e32 v130, v122, v122
	v_fmac_f32_e32 v130, v124, v124
	v_fmac_f32_e32 v130, v125, v125
	v_fmac_f32_e32 v130, v114, v114
	v_fmac_f32_e32 v130, v115, v115
	v_fmac_f32_e32 v130, v116, v116
	v_fmac_f32_e32 v130, v117, v117
	v_mov_b32_e32 v133, v130
	s_nop 1
	v_permlane16_swap_b32_e32 v133, v130
	v_cmp_lt_i32_e32 vcc, v134, v132
	v_add_f32_e32 v130, v130, v133
	v_cndmask_b32_e32 v132, v220, v134, vcc
	v_lshlrev_b32_e32 v157, 2, v132
	v_mov_b32_e32 v132, v130
	s_nop 1
	v_permlane32_swap_b32_e32 v132, v130
	v_add_f32_e32 v132, v130, v132
	s_and_saveexec_b64 s[34:35], s[4:5]
	ds_write_b32 v221, v132
	s_or_b64 exec, exec, s[34:35]
	v_mul_f32_e32 v130, v107, v107
	v_fmac_f32_e32 v130, v106, v106
	v_fmac_f32_e32 v130, v108, v108
	v_fmac_f32_e32 v130, v109, v109
	v_fmac_f32_e32 v130, v98, v98
	v_fmac_f32_e32 v130, v99, v99
	v_fmac_f32_e32 v130, v100, v100
	v_fmac_f32_e32 v130, v101, v101
	v_mov_b32_e32 v133, v130
	s_nop 1
	v_permlane16_swap_b32_e32 v133, v130
	v_add_f32_e32 v130, v130, v133
	v_mov_b32_e32 v133, v130
	s_nop 1
	v_permlane32_swap_b32_e32 v133, v130
	v_add_f32_e32 v133, v130, v133
	s_and_saveexec_b64 s[34:35], s[4:5]
	ds_write_b32 v221, v133 offset:64
	s_or_b64 exec, exec, s[34:35]
	v_mul_f32_e32 v130, v91, v91
	v_fmac_f32_e32 v130, v90, v90
	v_fmac_f32_e32 v130, v92, v92
	v_fmac_f32_e32 v130, v93, v93
	v_fmac_f32_e32 v130, v82, v82
	v_fmac_f32_e32 v130, v83, v83
	v_fmac_f32_e32 v130, v84, v84
	v_fmac_f32_e32 v130, v85, v85
	v_mov_b32_e32 v134, v130
	s_nop 1
	v_permlane16_swap_b32_e32 v134, v130
	v_add_f32_e32 v130, v130, v134
	v_mov_b32_e32 v134, v130
	s_nop 1
	v_permlane32_swap_b32_e32 v134, v130
	v_add_f32_e32 v168, v130, v134
	s_and_saveexec_b64 s[34:35], s[4:5]
	ds_write_b32 v221, v168 offset:128
	s_or_b64 exec, exec, s[34:35]
	v_mul_f32_e32 v130, v75, v75
	v_fmac_f32_e32 v130, v74, v74
	v_fmac_f32_e32 v130, v76, v76
	v_fmac_f32_e32 v130, v77, v77
	v_fmac_f32_e32 v130, v66, v66
	v_fmac_f32_e32 v130, v67, v67
	v_fmac_f32_e32 v130, v68, v68
	v_fmac_f32_e32 v130, v69, v69
	v_mov_b32_e32 v134, v130
	s_nop 1
	v_permlane16_swap_b32_e32 v134, v130
	v_add_f32_e32 v130, v130, v134
	v_mov_b32_e32 v134, v130
	s_nop 1
	v_permlane32_swap_b32_e32 v134, v130
	v_add_f32_e32 v169, v130, v134
	s_and_saveexec_b64 s[34:35], s[4:5]
	ds_write_b32 v221, v169 offset:192
	s_or_b64 exec, exec, s[34:35]
	v_mul_f32_e32 v130, v59, v59
	v_fmac_f32_e32 v130, v58, v58
	v_fmac_f32_e32 v130, v60, v60
	v_fmac_f32_e32 v130, v61, v61
	v_fmac_f32_e32 v130, v50, v50
	v_fmac_f32_e32 v130, v51, v51
	v_fmac_f32_e32 v130, v52, v52
	v_fmac_f32_e32 v130, v53, v53
	v_mov_b32_e32 v134, v130
	s_nop 1
	v_permlane16_swap_b32_e32 v134, v130
	v_add_f32_e32 v130, v130, v134
	v_mov_b32_e32 v134, v130
	s_nop 1
	v_permlane32_swap_b32_e32 v134, v130
	v_add_f32_e32 v172, v130, v134
	s_and_saveexec_b64 s[34:35], s[4:5]
	ds_write_b32 v254, v172
	s_or_b64 exec, exec, s[34:35]
	v_mul_f32_e32 v130, v43, v43
	v_fmac_f32_e32 v130, v42, v42
	v_fmac_f32_e32 v130, v44, v44
	v_fmac_f32_e32 v130, v45, v45
	v_fmac_f32_e32 v130, v34, v34
	v_fmac_f32_e32 v130, v35, v35
	v_fmac_f32_e32 v130, v36, v36
	v_fmac_f32_e32 v130, v37, v37
	v_mov_b32_e32 v134, v130
	s_nop 1
	v_permlane16_swap_b32_e32 v134, v130
	v_add_f32_e32 v130, v130, v134
	v_mov_b32_e32 v134, v130
	s_nop 1
	v_permlane32_swap_b32_e32 v134, v130
	v_add_f32_e32 v173, v130, v134
	s_and_saveexec_b64 s[34:35], s[4:5]
	ds_write_b32 v221, v173 offset:320
	s_or_b64 exec, exec, s[34:35]
	v_mul_f32_e32 v130, v27, v27
	v_fmac_f32_e32 v130, v26, v26
	v_fmac_f32_e32 v130, v28, v28
	v_fmac_f32_e32 v130, v29, v29
	v_fmac_f32_e32 v130, v18, v18
	v_fmac_f32_e32 v130, v19, v19
	v_fmac_f32_e32 v130, v20, v20
	v_fmac_f32_e32 v130, v21, v21
	v_mov_b32_e32 v134, v130
	s_nop 1
	v_permlane16_swap_b32_e32 v134, v130
	v_add_f32_e32 v130, v130, v134
	v_mov_b32_e32 v134, v130
	s_nop 1
	v_permlane32_swap_b32_e32 v134, v130
	v_add_f32_e32 v174, v130, v134
	s_and_saveexec_b64 s[34:35], s[4:5]
	ds_write_b32 v221, v174 offset:384
	s_or_b64 exec, exec, s[34:35]
	v_mul_f32_e32 v130, v11, v11
	v_fmac_f32_e32 v130, v10, v10
	v_fmac_f32_e32 v130, v12, v12
	v_fmac_f32_e32 v130, v13, v13
	v_fmac_f32_e32 v130, v2, v2
	v_fmac_f32_e32 v130, v3, v3
	v_fmac_f32_e32 v130, v4, v4
	v_fmac_f32_e32 v130, v5, v5
	v_mov_b32_e32 v134, v130
	s_nop 1
	v_permlane16_swap_b32_e32 v134, v130
	v_add_f32_e32 v130, v130, v134
	v_mov_b32_e32 v134, v130
	s_nop 1
	v_permlane32_swap_b32_e32 v134, v130
	v_add_f32_e32 v175, v130, v134
	s_and_saveexec_b64 s[34:35], s[4:5]
	ds_write_b32 v221, v175 offset:448
	s_or_b64 exec, exec, s[34:35]
	v_mul_f32_e32 v130, v127, v127
	v_fmac_f32_e32 v130, v126, v126
	v_fmac_f32_e32 v130, v128, v128
	v_fmac_f32_e32 v130, v129, v129
	v_fmac_f32_e32 v130, v118, v118
	v_fmac_f32_e32 v130, v119, v119
	v_fmac_f32_e32 v130, v120, v120
	v_fmac_f32_e32 v130, v121, v121
	v_mov_b32_e32 v134, v130
	s_nop 1
	v_permlane16_swap_b32_e32 v134, v130
	v_add_f32_e32 v130, v130, v134
	v_mov_b32_e32 v134, v130
	s_nop 1
	v_permlane32_swap_b32_e32 v134, v130
	v_add_f32_e32 v136, v130, v134
	s_and_saveexec_b64 s[34:35], s[4:5]
	ds_write_b32 v208, v136
	s_or_b64 exec, exec, s[34:35]
	v_mul_f32_e32 v130, v111, v111
	v_fmac_f32_e32 v130, v110, v110
	v_fmac_f32_e32 v130, v112, v112
	v_fmac_f32_e32 v130, v113, v113
	v_fmac_f32_e32 v130, v102, v102
	v_fmac_f32_e32 v130, v103, v103
	v_fmac_f32_e32 v130, v104, v104
	v_fmac_f32_e32 v130, v105, v105
	v_mov_b32_e32 v134, v130
	s_nop 1
	v_permlane16_swap_b32_e32 v134, v130
	v_add_f32_e32 v130, v130, v134
	v_mov_b32_e32 v134, v130
	s_nop 1
	v_permlane32_swap_b32_e32 v134, v130
	v_add_f32_e32 v137, v130, v134
	s_and_saveexec_b64 s[34:35], s[4:5]
	ds_write_b32 v221, v137 offset:576
	s_or_b64 exec, exec, s[34:35]
	v_mul_f32_e32 v130, v95, v95
	v_fmac_f32_e32 v130, v94, v94
	v_fmac_f32_e32 v130, v96, v96
	v_fmac_f32_e32 v130, v97, v97
	v_fmac_f32_e32 v130, v86, v86
	v_fmac_f32_e32 v130, v87, v87
	v_fmac_f32_e32 v130, v88, v88
	v_fmac_f32_e32 v130, v89, v89
	v_mov_b32_e32 v134, v130
	s_nop 1
	v_permlane16_swap_b32_e32 v134, v130
	v_add_f32_e32 v130, v130, v134
	v_mov_b32_e32 v134, v130
	s_nop 1
	v_permlane32_swap_b32_e32 v134, v130
	v_add_f32_e32 v158, v130, v134
	s_and_saveexec_b64 s[34:35], s[4:5]
	ds_write_b32 v221, v158 offset:640
	s_or_b64 exec, exec, s[34:35]
	v_mul_f32_e32 v130, v79, v79
	v_fmac_f32_e32 v130, v78, v78
	v_fmac_f32_e32 v130, v80, v80
	v_fmac_f32_e32 v130, v81, v81
	v_fmac_f32_e32 v130, v70, v70
	v_fmac_f32_e32 v130, v71, v71
	v_fmac_f32_e32 v130, v72, v72
	v_fmac_f32_e32 v130, v73, v73
	v_mov_b32_e32 v134, v130
	s_nop 1
	v_permlane16_swap_b32_e32 v134, v130
	v_add_f32_e32 v130, v130, v134
	v_mov_b32_e32 v134, v130
	s_nop 1
	v_permlane32_swap_b32_e32 v134, v130
	v_add_f32_e32 v159, v130, v134
	s_and_saveexec_b64 s[34:35], s[4:5]
	ds_write_b32 v221, v159 offset:704
	s_or_b64 exec, exec, s[34:35]
	v_mul_f32_e32 v130, v63, v63
	v_fmac_f32_e32 v130, v62, v62
	v_fmac_f32_e32 v130, v64, v64
	v_fmac_f32_e32 v130, v65, v65
	v_fmac_f32_e32 v130, v54, v54
	v_fmac_f32_e32 v130, v55, v55
	v_fmac_f32_e32 v130, v56, v56
	v_fmac_f32_e32 v130, v57, v57
	v_mov_b32_e32 v134, v130
	s_nop 1
	v_permlane16_swap_b32_e32 v134, v130
	v_add_f32_e32 v130, v130, v134
	v_mov_b32_e32 v134, v130
	s_nop 1
	v_permlane32_swap_b32_e32 v134, v130
	v_add_f32_e32 v134, v130, v134
	s_and_saveexec_b64 s[34:35], s[4:5]
	ds_write_b32 v198, v134
	s_or_b64 exec, exec, s[34:35]
	v_mul_f32_e32 v130, v47, v47
	v_fmac_f32_e32 v130, v46, v46
	v_fmac_f32_e32 v130, v48, v48
	v_fmac_f32_e32 v130, v49, v49
	v_fmac_f32_e32 v130, v38, v38
	v_fmac_f32_e32 v130, v39, v39
	v_fmac_f32_e32 v130, v40, v40
	v_fmac_f32_e32 v130, v41, v41
	v_mov_b32_e32 v135, v130
	s_nop 1
	v_permlane16_swap_b32_e32 v135, v130
	v_add_f32_e32 v130, v130, v135
	v_mov_b32_e32 v135, v130
	s_nop 1
	v_permlane32_swap_b32_e32 v135, v130
	v_add_f32_e32 v135, v130, v135
	s_and_saveexec_b64 s[34:35], s[4:5]
	ds_write_b32 v221, v135 offset:832
	s_or_b64 exec, exec, s[34:35]
	v_mul_f32_e32 v130, v31, v31
	v_fmac_f32_e32 v130, v30, v30
	v_fmac_f32_e32 v130, v32, v32
	v_fmac_f32_e32 v130, v33, v33
	v_fmac_f32_e32 v130, v22, v22
	v_fmac_f32_e32 v130, v23, v23
	v_fmac_f32_e32 v130, v24, v24
	v_fmac_f32_e32 v130, v25, v25
	v_mov_b32_e32 v160, v130
	s_nop 1
	v_permlane16_swap_b32_e32 v160, v130
	v_add_f32_e32 v130, v130, v160
	v_mov_b32_e32 v160, v130
	s_nop 1
	v_permlane32_swap_b32_e32 v160, v130
	v_add_f32_e32 v130, v130, v160
	s_and_saveexec_b64 s[34:35], s[4:5]
	ds_write_b32 v221, v130 offset:896
	s_or_b64 exec, exec, s[34:35]
	v_mul_f32_e32 v160, v15, v15
	v_fmac_f32_e32 v160, v14, v14
	v_fmac_f32_e32 v160, v16, v16
	v_fmac_f32_e32 v160, v17, v17
	v_fmac_f32_e32 v160, v6, v6
	v_fmac_f32_e32 v160, v7, v7
	v_fmac_f32_e32 v160, v8, v8
	v_fmac_f32_e32 v160, v9, v9
	v_mov_b32_e32 v131, v160
	s_nop 1
	v_permlane16_swap_b32_e32 v131, v160
	v_add_f32_e32 v131, v160, v131
	v_mov_b32_e32 v157, v131
	s_nop 1
	v_permlane32_swap_b32_e32 v157, v131
	v_add_f32_e32 v131, v131, v157
	s_and_saveexec_b64 s[34:35], s[4:5]
	ds_write_b32 v196, v131
	s_or_b64 exec, exec, s[34:35]
	v_lshl_add_u64 v[160:161], s[42:43], 0, v[146:147]
	v_mov_b32_e32 v157, v147
	v_lshl_add_u64 v[160:161], v[160:161], 0, v[156:157]
	v_bfe_u32 v157, v0, 7, 1
	v_mul_u32_u24_e32 v157, s70, v157
	v_lshlrev_b32_e32 v162, 2, v157
	v_mov_b32_e32 v163, v147
	v_lshl_add_u64 v[170:171], v[160:161], 0, v[162:163]
	s_waitcnt vmcnt(0) lgkmcnt(0)
	s_barrier
	v_mov_b32_e32 v160, v200
	v_mov_b32_e32 v161, v201
	v_mov_b32_e32 v162, v202
	v_mov_b32_e32 v163, v203
	v_mov_b32_e32 v176, v204
	v_mov_b32_e32 v177, v205
	v_mov_b32_e32 v178, v206
	v_mov_b32_e32 v179, v207
	s_mov_b32 s14, 0x358637bd
	s_lshl_b32 s70, s70, 3
	v_lshl_add_u64 v[170:171], v[170:171], 0, s[70:71]
	s_waitcnt vmcnt(1)
	v_pk_mul_f32 v[162:163], s[30:31], v[162:163] op_sel_hi:[0,1]
	s_waitcnt vmcnt(0)
	v_pk_mul_f32 v[166:167], v[176:177], s[30:31] op_sel_hi:[1,0]
	ds_read2_b32 v[176:177], v211 offset1:16
	v_pk_mul_f32 v[164:165], v[178:179], s[30:31] op_sel_hi:[1,0]
	v_pk_mul_f32 v[160:161], s[30:31], v[160:161] op_sel_hi:[0,1]
	s_waitcnt lgkmcnt(0)
	v_pk_add_f32 v[176:177], v[132:133], v[176:177]
	v_mov_b64_e32 v[132:133], s[14:15]
	v_pk_fma_f32 v[176:177], v[176:177], s[8:9], v[132:133] op_sel_hi:[1,0,0]
	s_nop 0
	v_mul_f32_e32 v157, 0x4b800000, v176
	v_cmp_gt_f32_e64 s[42:43], s11, v176
	v_cmp_gt_f32_e32 vcc, s11, v177
	s_nop 0
	v_cndmask_b32_e64 v157, v176, v157, s[42:43]
	v_rsq_f32_e32 v176, v157
	v_mul_f32_e32 v157, 0x4b800000, v177
	v_cndmask_b32_e32 v157, v177, v157, vcc
	v_rsq_f32_e32 v177, v157
	s_nop 0
	v_pk_mul_f32 v[178:179], v[176:177], s[10:11] op_sel_hi:[1,0]
	s_nop 0
	v_cndmask_b32_e64 v190, v176, v178, s[42:43]
	v_cndmask_b32_e32 v191, v177, v179, vcc
	ds_read2_b32 v[176:177], v211 offset0:32 offset1:48
	s_waitcnt lgkmcnt(0)
	v_pk_add_f32 v[168:169], v[168:169], v[176:177]
	s_nop 0
	v_pk_fma_f32 v[168:169], v[168:169], s[8:9], v[132:133] op_sel_hi:[1,0,0]
	s_nop 0
	v_mul_f32_e32 v157, 0x4b800000, v168
	v_cmp_gt_f32_e64 s[42:43], s11, v168
	v_cmp_gt_f32_e32 vcc, s11, v169
	s_nop 0
	v_cndmask_b32_e64 v157, v168, v157, s[42:43]
	v_rsq_f32_e32 v168, v157
	v_mul_f32_e32 v157, 0x4b800000, v169
	v_cndmask_b32_e32 v157, v169, v157, vcc
	v_rsq_f32_e32 v169, v157
	s_nop 0
	v_pk_mul_f32 v[176:177], v[168:169], s[10:11] op_sel_hi:[1,0]
	s_nop 0
	v_cndmask_b32_e64 v186, v168, v176, s[42:43]
	v_cndmask_b32_e32 v187, v169, v177, vcc
	ds_read_b32 v168, v212
	ds_read2_b32 v[176:177], v211 offset0:80 offset1:96
	ds_read2_b32 v[178:179], v211 offset0:112 offset1:144
	s_waitcnt lgkmcnt(1)
	v_mov_b32_e32 v169, v176
	v_pk_add_f32 v[168:169], v[172:173], v[168:169]
	s_nop 0
	v_pk_fma_f32 v[168:169], v[168:169], s[8:9], v[132:133] op_sel_hi:[1,0,0]
	s_nop 0
	v_mul_f32_e32 v157, 0x4b800000, v168
	v_cmp_gt_f32_e64 s[42:43], s11, v168
	v_cmp_gt_f32_e32 vcc, s11, v169
	s_nop 0
	v_cndmask_b32_e64 v157, v168, v157, s[42:43]
	v_rsq_f32_e32 v168, v157
	v_mul_f32_e32 v157, 0x4b800000, v169
	v_cndmask_b32_e32 v157, v169, v157, vcc
	v_rsq_f32_e32 v169, v157
	s_nop 0
	v_pk_mul_f32 v[172:173], v[168:169], s[10:11] op_sel_hi:[1,0]
	s_nop 0
	v_cndmask_b32_e64 v182, v168, v172, s[42:43]
	v_cndmask_b32_e32 v183, v169, v173, vcc
	v_mov_b32_e32 v168, v177
	s_waitcnt lgkmcnt(0)
	v_mov_b32_e32 v169, v178
	v_pk_add_f32 v[168:169], v[174:175], v[168:169]
	s_nop 0
	v_pk_fma_f32 v[168:169], v[168:169], s[8:9], v[132:133] op_sel_hi:[1,0,0]
	s_nop 0
	v_mul_f32_e32 v157, 0x4b800000, v168
	v_cmp_gt_f32_e64 s[42:43], s11, v168
	v_cmp_gt_f32_e32 vcc, s11, v169
	s_nop 0
	v_cndmask_b32_e64 v157, v168, v157, s[42:43]
	v_rsq_f32_e32 v168, v157
	v_mul_f32_e32 v157, 0x4b800000, v169
	v_cndmask_b32_e32 v157, v169, v157, vcc
	v_rsq_f32_e32 v169, v157
	s_nop 0
	v_pk_mul_f32 v[172:173], v[168:169], s[10:11] op_sel_hi:[1,0]
	s_nop 0
	v_cndmask_b32_e64 v168, v168, v172, s[42:43]
	v_cndmask_b32_e32 v169, v169, v173, vcc
	v_mov_b32_e32 v192, v216
	v_mov_b32_e32 v193, v217
	v_mov_b32_e32 v194, v218
	v_mov_b32_e32 v195, v219
	s_nop 0
	v_mov_b32_e32 v170, v224
	v_mov_b32_e32 v171, v225
	v_mov_b32_e32 v172, v226
	v_mov_b32_e32 v173, v227
	ds_read_b32 v178, v213
	s_waitcnt lgkmcnt(0)
	v_pk_add_f32 v[136:137], v[136:137], v[178:179]
	s_nop 0
	v_pk_fma_f32 v[136:137], v[136:137], s[8:9], v[132:133] op_sel_hi:[1,0,0]
	s_waitcnt vmcnt(1)
	v_pk_mul_f32 v[176:177], s[30:31], v[192:193] op_sel_hi:[0,1]
	v_mul_f32_e32 v157, 0x4b800000, v136
	v_cmp_gt_f32_e64 s[42:43], s11, v136
	v_cmp_gt_f32_e32 vcc, s11, v137
	s_waitcnt vmcnt(0)
	v_pk_mul_f32 v[174:175], s[30:31], v[172:173] op_sel_hi:[0,1]
	v_cndmask_b32_e64 v136, v136, v157, s[42:43]
	v_mul_f32_e32 v157, 0x4b800000, v137
	v_cndmask_b32_e32 v137, v137, v157, vcc
	v_rsq_f32_e32 v136, v136
	v_rsq_f32_e32 v137, v137
	v_pk_mul_f32 v[172:173], s[30:31], v[170:171] op_sel_hi:[0,1]
	v_pk_mul_f32 v[170:171], s[30:31], v[194:195] op_sel_hi:[0,1]
	v_pk_mul_f32 v[178:179], v[136:137], s[10:11] op_sel_hi:[1,0]
	s_nop 0
	v_cndmask_b32_e64 v192, v136, v178, s[42:43]
	v_cndmask_b32_e32 v193, v137, v179, vcc
	ds_read2_b32 v[136:137], v211 offset0:160 offset1:176
	s_waitcnt lgkmcnt(0)
	v_pk_add_f32 v[136:137], v[158:159], v[136:137]
	s_nop 0
	v_pk_fma_f32 v[136:137], v[136:137], s[8:9], v[132:133] op_sel_hi:[1,0,0]
	s_nop 0
	v_mul_f32_e32 v157, 0x4b800000, v136
	v_cmp_gt_f32_e64 s[42:43], s11, v136
	v_cmp_gt_f32_e32 vcc, s11, v137
	s_nop 0
	v_cndmask_b32_e64 v136, v136, v157, s[42:43]
	v_mul_f32_e32 v157, 0x4b800000, v137
	v_cndmask_b32_e32 v137, v137, v157, vcc
	v_rsq_f32_e32 v136, v136
	v_rsq_f32_e32 v137, v137
	s_nop 0
	v_pk_mul_f32 v[158:159], v[136:137], s[10:11] op_sel_hi:[1,0]
	s_nop 0
	v_cndmask_b32_e64 v188, v136, v158, s[42:43]
	v_cndmask_b32_e32 v189, v137, v159, vcc
	ds_read_b32 v158, v214
	ds_read2_b32 v[136:137], v211 offset0:208 offset1:224
	s_waitcnt lgkmcnt(0)
	v_mov_b32_e32 v159, v136
	v_pk_add_f32 v[134:135], v[134:135], v[158:159]
	s_nop 0
	v_pk_fma_f32 v[134:135], v[134:135], s[8:9], v[132:133] op_sel_hi:[1,0,0]
	s_nop 0
	v_mul_f32_e32 v136, 0x4b800000, v134
	v_cmp_gt_f32_e64 s[42:43], s11, v134
	v_cmp_gt_f32_e32 vcc, s11, v135
	s_nop 0
	v_cndmask_b32_e64 v134, v134, v136, s[42:43]
	v_mul_f32_e32 v136, 0x4b800000, v135
	v_cndmask_b32_e32 v135, v135, v136, vcc
	v_rsq_f32_e32 v134, v134
	v_rsq_f32_e32 v135, v135
	s_nop 0
	v_pk_mul_f32 v[158:159], v[134:135], s[10:11] op_sel_hi:[1,0]
	s_nop 0
	v_cndmask_b32_e32 v185, v135, v159, vcc
	ds_read_b32 v135, v215
	v_cndmask_b32_e64 v184, v134, v158, s[42:43]
	v_mov_b32_e32 v134, v137
	s_waitcnt lgkmcnt(0)
	v_pk_add_f32 v[130:131], v[130:131], v[134:135]
	s_nop 0
	v_pk_fma_f32 v[130:131], v[130:131], s[8:9], v[132:133] op_sel_hi:[1,0,0]
	s_nop 0
	v_mul_f32_e32 v132, 0x4b800000, v130
	v_cmp_gt_f32_e64 s[42:43], s11, v130
	v_cmp_gt_f32_e32 vcc, s11, v131
	s_nop 0
	v_cndmask_b32_e64 v130, v130, v132, s[42:43]
	v_mul_f32_e32 v132, 0x4b800000, v131
	v_cndmask_b32_e32 v131, v131, v132, vcc
	v_rsq_f32_e32 v130, v130
	v_rsq_f32_e32 v131, v131
	s_nop 0
	v_pk_mul_f32 v[132:133], v[130:131], s[10:11] op_sel_hi:[1,0]
	s_nop 0
	v_cndmask_b32_e64 v180, v130, v132, s[42:43]
	v_cndmask_b32_e32 v181, v131, v133, vcc
